# phase 2 work assignment: balanced unit order (one q unit + three light units on 4-unit workgroups, two q + one light on 3-unit workgroups) and the meta-row units on workgroups 200..255
# speedup vs baseline: 1.0051x; 1.0017x over previous
.LBB0_367:
	s_cmp_lt_i32 s22, 3
	s_cselect_b64 s[0:1], -1, 0
	s_cmp_gt_i32 s23, 2
	s_cselect_b64 s[2:3], -1, 0
	s_and_b64 s[0:1], s[0:1], s[2:3]
	s_andn2_b64 vcc, exec, s[0:1]
	s_cbranch_vccnz .LBB0_717
	s_cmpk_lt_u32 s96, 0x380
	s_cselect_b64 s[2:3], -1, 0
	s_cmpk_gt_u32 s96, 0x37f
	v_readfirstlane_b32 s13, v208
	s_cbranch_scc1 .LBB0_373
	s_and_b32 s0, s96, 7
	s_lshr_b32 s1, s96, 3
	s_cmpk_lg_i32 s82, 0x100
	s_cbranch_scc1 .Lp2map_a_done
	s_cmp_lt_u32 s1, 16
	s_cbranch_scc1 .Lp2map_a_q
	s_lshl_b32 s1, s1, 1
	s_add_i32 s1, s1, -16
.Lp2map_a_q:
	s_mul_i32 s4, s1, 43
	s_lshr_b32 s4, s4, 9
	s_mul_i32 s5, s4, 12
	s_sub_i32 s1, s1, s5
	s_mul_i32 s4, s4, 28
	s_add_i32 s1, s4, s1
.Lp2map_a_done:
	s_mulk_i32 s0, 0x70
	s_add_i32 s0, s0, s1
	s_bfe_u32 s1, s0, 0x100002
	s_mulk_i32 s1, 0x4925
	s_lshr_b32 s1, s1, 17
	s_lshl_b32 s5, s1, 2
	s_mul_i32 s1, s1, 28
	s_sub_i32 s0, s0, s1
	s_and_b32 s1, s0, 3
	s_and_b32 s4, s0, 0xffff
	s_or_b32 s9, s1, s5
	s_bfe_u32 s11, s0, 0xe0002
	s_cmp_gt_u32 s4, 11
	s_mul_i32 s12, s9, 0x180000
	s_cbranch_scc0 .LBB0_374
	s_add_u32 s0, s20, s12
	s_addc_u32 s1, s21, 0
	s_add_u32 s0, s0, 0x4f61200
	s_addc_u32 s1, s1, 0
	s_cmp_gt_u32 s4, 19
	s_mov_b32 s5, 0
	s_cbranch_scc0 .LBB0_660
	s_add_i32 s4, s11, -5
	s_lshl_b64 s[4:5], s[4:5], 17
	s_add_u32 s4, s20, s4
	s_addc_u32 s5, s21, s5
	s_add_u32 s6, s4, 0x6a0000
	s_addc_u32 s7, s5, 0
	s_lshl_b32 s4, s11, 8
	s_add_i32 s10, s4, 0xfffffb00
	s_lshl_b32 s89, s9, 8
	s_mov_b32 s90, 1
	s_cbranch_execz .LBB0_661
	s_mov_b32 s90, 2
	s_movk_i32 s8, 0x1800
	s_movk_i32 s56, 0x200
	s_cbranch_execz .LBB0_375
	s_branch .LBB0_376

.LBB0_381:
	s_add_i32 s88, s88, 1
	s_mul_i32 s5, s88, s82
	s_mul_hi_u32 s4, s88, s82
	s_add_u32 s58, s5, s96
	s_addc_u32 s59, s4, 0
	v_cmp_gt_u64_e64 s[4:5], s[58:59], v[142:143]
	s_and_b64 vcc, exec, s[4:5]
	s_mov_b32 s84, s8
	s_mov_b32 s85, s56
	s_cbranch_vccnz .LBB0_389
	s_and_b32 s9, s58, 7
	s_lshr_b32 s11, s58, 3
	s_cmpk_lg_i32 s82, 0x100
	s_cbranch_scc1 .Lp2map_b_done
	s_and_b32 s14, s11, 31
	s_lshr_b32 s15, s11, 5
	s_cmp_lt_u32 s14, 16
	s_cbranch_scc0 .Lp2map_b_hi
	s_cmp_eq_u32 s15, 0
	s_cbranch_scc1 .Lp2map_b_q
	s_add_i32 s15, s15, -1
	s_mul_i32 s15, s15, 28
	s_add_i32 s11, s15, s14
	s_add_i32 s11, s11, 12
	s_branch .Lp2map_b_done
.Lp2map_b_hi:
	s_add_i32 s14, s14, -16
	s_cmp_eq_u32 s15, 2
	s_cbranch_scc0 .Lp2map_b_hq
	s_add_i32 s11, s14, 0x60
	s_branch .Lp2map_b_done
.Lp2map_b_hq:
	s_lshl_b32 s14, s14, 1
	s_add_i32 s14, s14, s15
	s_add_i32 s14, s14, 16
.Lp2map_b_q:
	s_mul_i32 s15, s14, 43
	s_lshr_b32 s15, s15, 9
	s_mul_i32 s25, s15, 12
	s_sub_i32 s14, s14, s25
	s_mul_i32 s15, s15, 28
	s_add_i32 s11, s15, s14
.Lp2map_b_done:
	s_mulk_i32 s9, 0x70
	s_add_i32 s9, s9, s11
	s_bfe_u32 s11, s9, 0xe0002
	s_mulk_i32 s11, 0x4925
	s_lshr_b32 s11, s11, 17
	s_lshl_b32 s14, s11, 2
	s_mul_i32 s11, s11, 28
	s_sub_i32 s11, s9, s11
	s_and_b32 s9, s11, 3
	s_or_b32 s9, s9, s14
	s_and_b32 s9, s9, 0x7fff
	s_bfe_u32 s14, s11, 0xe0002
	s_and_b32 s35, s11, 0xffff
	s_mov_b64 s[58:59], -1
	s_cmp_gt_u32 s35, 11
	s_mul_hi_u32 s15, s9, 0x180000
	s_mul_i32 s25, s9, 0x180000
	s_cbranch_scc0 .LBB0_387
	v_readlane_b32 s11, v247, 20
	s_add_u32 s52, s11, s25
	v_readlane_b32 s11, v247, 21
	s_addc_u32 s53, s11, s15
	s_cmp_gt_u32 s35, 19
	s_cbranch_scc0 .LBB0_385
	s_add_i32 s92, s14, -5
	s_lshl_b64 s[54:55], s[92:93], 17
	v_readlane_b32 s11, v247, 22
	s_add_u32 s54, s11, s54
	v_readlane_b32 s11, v247, 24
	s_addc_u32 s55, s11, s55
	s_lshl_b32 s11, s14, 8
	s_addk_i32 s11, 0xfb00
	s_lshl_b32 s86, s9, 8
	s_mov_b64 s[58:59], 0

.LBB0_435:
	s_sub_i32 s0, s96, 0xc8
	s_cmpk_eq_i32 s82, 0x100
	s_cselect_b32 s0, s0, s96
	s_cmp_gt_i32 s0, 55
	s_cbranch_scc1 .LBB0_460
	s_cmp_lt_i32 s0, 0
	s_cbranch_scc1 .LBB0_460
	v_and_b32_e32 v2, 63, v208
	v_lshl_add_u32 v44, v2, 4, 0
	v_mul_u32_u24_e32 v2, 0xc00, v1
	v_lshrrev_b32_e32 v6, 1, v208
	v_lshlrev_b32_e32 v10, 1, v2
	v_mov_b32_e32 v11, 0
	v_and_b32_e32 v6, 24, v6
	v_lshl_add_u64 v[2:3], s[20:21], 0, v[10:11]
	s_mov_b64 s[2:3], 0x19ff1a00
	v_lshlrev_b32_e32 v8, 1, v6
	v_mov_b32_e32 v9, v11
	v_lshl_add_u64 v[4:5], v[2:3], 0, s[2:3]
	v_lshlrev_b32_e32 v18, 6, v209
	v_mov_b32_e32 v19, v11
	v_lshl_add_u64 v[2:3], v[2:3], 0, v[8:9]
	s_add_u32 s4, s20, 0x19fc0400
	v_bfe_u32 v7, v208, 4, 2
	v_lshl_add_u64 v[2:3], v[2:3], 0, v[18:19]
	s_mov_b64 s[6:7], 0x19ff1800
	s_addc_u32 s5, s21, 0
	v_lshlrev_b32_e32 v14, 6, v7
	v_mov_b32_e32 v15, v11
	v_lshl_add_u64 v[16:17], v[2:3], 0, s[6:7]
	v_lshl_add_u64 v[2:3], s[20:21], 0, v[8:9]
	s_add_u32 s8, s20, 0x19fa0000
	v_lshl_add_u64 v[12:13], v[4:5], 0, v[8:9]
	v_lshl_add_u64 v[14:15], v[4:5], 0, v[14:15]
	v_lshlrev_b32_e32 v45, 2, v7
	v_lshl_add_u64 v[2:3], v[2:3], 0, v[18:19]
	s_mov_b64 s[6:7], 0x600000
	v_lshlrev_b32_e32 v4, 2, v1
	s_addc_u32 s9, s21, 0
	v_lshl_add_u64 v[12:13], v[12:13], 0, v[18:19]
	v_lshl_add_u64 v[18:19], v[2:3], 0, s[6:7]
	v_or_b32_e32 v47, 1, v45
	v_lshl_or_b32 v2, v7, 8, v4
	v_mov_b32_e32 v3, v11
	v_or_b32_e32 v49, 2, v45
	v_lshl_add_u64 v[20:21], s[8:9], 0, v[2:3]
	v_lshl_add_u64 v[22:23], s[4:5], 0, v[2:3]
	v_lshl_or_b32 v2, v47, 6, v4
	v_or_b32_e32 v51, 3, v45
	v_lshl_add_u64 v[24:25], s[8:9], 0, v[2:3]
	v_lshl_add_u64 v[26:27], s[4:5], 0, v[2:3]
	v_lshl_or_b32 v2, v49, 6, v4
	v_lshl_add_u64 v[28:29], s[8:9], 0, v[2:3]
	v_lshl_add_u64 v[30:31], s[4:5], 0, v[2:3]
	v_lshl_or_b32 v2, v51, 6, v4
	v_lshlrev_b32_e32 v38, 5, v209
	v_lshlrev_b32_e32 v39, 11, v209
	s_add_u32 s6, s20, 0x1a00c800
	v_lshl_add_u64 v[32:33], s[8:9], 0, v[2:3]
	v_lshl_add_u64 v[34:35], s[4:5], 0, v[2:3]
	v_lshl_or_b32 v10, v7, 7, v10
	v_mbcnt_lo_u32_b32 v2, -1, 0
	s_mov_b32 s1, 0
	v_cmp_gt_u32_e64 s[2:3], 64, v208
	s_addc_u32 s7, s21, 0
	v_lshlrev_b32_e32 v46, 11, v7
	v_lshlrev_b32_e32 v48, 9, v47
	v_lshlrev_b32_e32 v50, 9, v49
	v_lshlrev_b32_e32 v52, 9, v51
	v_mul_u32_u24_e32 v53, 0xc00, v7
	v_mul_u32_u24_e32 v54, 0x300, v47
	v_lshl_add_u64 v[36:37], s[20:21], 0, v[10:11]
	s_movk_i32 s12, 0xffd8
	s_mov_b32 s13, 0x6a0000
	v_lshlrev_b32_e32 v10, 1, v6
	v_lshlrev_b32_e32 v38, 1, v38
	s_movk_i32 s14, 0x2000
	v_mov_b32_e32 v55, 0x358637bd
	s_mov_b32 s15, 0x800000
	s_mov_b32 s24, 0x1a016800
	v_add_u32_e32 v56, v44, v39
	v_mbcnt_hi_u32_b32 v57, -1, v2
	s_sub_i32 s25, s96, 0xc8
	s_cmpk_eq_i32 s82, 0x100
	s_cselect_b32 s25, s25, s96
	s_branch .LBB0_440
